# grid barriers: XCD leaders add to TOP without return and poll TOP >= K*nXCD themselves (no TOPGEN hop, one atomic round trip less)
# speedup vs baseline: 1.0236x; 1.0085x over previous
; DI unsigned xb_ld(unsigned* p)              { return __hip_atomic_load(p, __ATOMIC_RELAXED, __HIP_MEMORY_SCOPE_AGENT); }
; DI unsigned xb_add(unsigned* p, unsigned v) { return __hip_atomic_fetch_add(p, v, __ATOMIC_RELAXED, __HIP_MEMORY_SCOPE_AGENT); }
; #define XB_SPIN(cond, bar) do { unsigned _sp = 0; while (cond) { __builtin_amdgcn_s_sleep(1); \
;     if ((++_sp & 255u) == 0u) { if (xb_ld(&(bar)[XB_TMO])) break; if (_sp > XB_SPIN_CAP) { atomicAdd(&(bar)[XB_TMO], 1u); break; } } } } while (0)
; DI void xcd_barrier(unsigned* bar, volatile __attribute__((address_space(3))) unsigned* st) {
;     ...
;             __builtin_amdgcn_fence(__ATOMIC_RELEASE, "agent");
;             asm volatile("s_waitcnt vmcnt(0)" ::: "memory");
;             const unsigned og = xb_add(&bar[XB_TOP], 1u);
;             const unsigned tg = og / nx;
;             if (og + 1u == (tg + 1u) * nx) xb_add(&bar[XB_TOPGEN], 1u);
;             else XB_SPIN(xb_ld(&bar[XB_TOPGEN]) == tg, bar);
;             __builtin_amdgcn_fence(__ATOMIC_ACQUIRE, "agent");
;             xb_add(&bar[XB_XGEN(x)], 1u);
.LBB0_164:
	s_andn2_saveexec_b64 s[6:7], s[6:7]
	s_cbranch_execz .LBB0_184
	s_mov_b64 s[6:7], exec
	buffer_wbl2 sc1
	s_waitcnt lgkmcnt(0)
	s_waitcnt vmcnt(0)
	v_mov_b32_e32 v2, 0x34e5000
	v_mov_b32_e32 v3, 1
	global_atomic_add v2, v3, s[70:71] offset:1280
	v_mul_u32_u24_e32 v4, 1, v1
.Ltopf_p1:
	global_load_dword v3, v2, s[70:71] offset:1280 sc1
	s_waitcnt vmcnt(0)
	v_cmp_lt_u32_e32 vcc, v3, v4
	s_cbranch_vccz .Ltopf_d1
	s_sleep 1
	s_branch .Ltopf_p1
.Ltopf_d1:
	s_mov_b64 s[6:7], exec
.LBB0_181:
	s_or_b64 exec, exec, s[6:7]
	s_mov_b64 s[6:7], exec
	v_mbcnt_lo_u32_b32 v0, s6, 0
	v_mbcnt_hi_u32_b32 v0, s7, v0
	v_cmp_eq_u32_e32 vcc, 0, v0
	s_waitcnt vmcnt(0)
	buffer_inv sc1
	s_and_saveexec_b64 s[8:9], vcc
	s_cbranch_execz .LBB0_183
	s_bcnt1_i32_b64 s3, s[6:7]
	v_mov_b32_e32 v0, 0x2000
	v_mov_b32_e32 v1, s3
	global_atomic_add v0, v1, s[4:5] offset:1024

; DI unsigned xb_ld(unsigned* p)              { return __hip_atomic_load(p, __ATOMIC_RELAXED, __HIP_MEMORY_SCOPE_AGENT); }
; DI unsigned xb_add(unsigned* p, unsigned v) { return __hip_atomic_fetch_add(p, v, __ATOMIC_RELAXED, __HIP_MEMORY_SCOPE_AGENT); }
; #define XB_SPIN(cond, bar) do { unsigned _sp = 0; while (cond) { __builtin_amdgcn_s_sleep(1); \
;     if ((++_sp & 255u) == 0u) { if (xb_ld(&(bar)[XB_TMO])) break; if (_sp > XB_SPIN_CAP) { atomicAdd(&(bar)[XB_TMO], 1u); break; } } } } while (0)
; DI void xcd_barrier(unsigned* bar, volatile __attribute__((address_space(3))) unsigned* st) {
;     ...
;             __builtin_amdgcn_fence(__ATOMIC_RELEASE, "agent");
;             asm volatile("s_waitcnt vmcnt(0)" ::: "memory");
;             const unsigned og = xb_add(&bar[XB_TOP], 1u);
;             const unsigned tg = og / nx;
;             if (og + 1u == (tg + 1u) * nx) xb_add(&bar[XB_TOPGEN], 1u);
;             else XB_SPIN(xb_ld(&bar[XB_TOPGEN]) == tg, bar);
.LBB0_254:
	s_andn2_saveexec_b64 s[8:9], s[8:9]
	s_cbranch_execz .LBB0_274
	s_mov_b64 s[8:9], exec
	buffer_wbl2 sc1
	s_waitcnt lgkmcnt(0)
	s_waitcnt vmcnt(0)
	v_mov_b32_e32 v2, 0x34e5000
	v_mov_b32_e32 v3, 1
	global_atomic_add v2, v3, s[70:71] offset:1280
	v_mul_u32_u24_e32 v4, 2, v1

; DI unsigned xb_ld(unsigned* p)              { return __hip_atomic_load(p, __ATOMIC_RELAXED, __HIP_MEMORY_SCOPE_AGENT); }
; DI unsigned xb_add(unsigned* p, unsigned v) { return __hip_atomic_fetch_add(p, v, __ATOMIC_RELAXED, __HIP_MEMORY_SCOPE_AGENT); }
; #define XB_SPIN(cond, bar) do { unsigned _sp = 0; while (cond) { __builtin_amdgcn_s_sleep(1); \
;     if ((++_sp & 255u) == 0u) { if (xb_ld(&(bar)[XB_TMO])) break; if (_sp > XB_SPIN_CAP) { atomicAdd(&(bar)[XB_TMO], 1u); break; } } } } while (0)
; DI void xcd_barrier(unsigned* bar, volatile __attribute__((address_space(3))) unsigned* st) {
;     ...
;             else XB_SPIN(xb_ld(&bar[XB_TOPGEN]) == tg, bar);
;             __builtin_amdgcn_fence(__ATOMIC_ACQUIRE, "agent");
;             xb_add(&bar[XB_XGEN(x)], 1u);
;             asm volatile("s_waitcnt vmcnt(0)" ::: "memory");
.Ltopf_d2:
	s_mov_b64 s[8:9], exec
.LBB0_271:
	s_or_b64 exec, exec, s[8:9]
	s_mov_b64 s[8:9], exec
	v_mbcnt_lo_u32_b32 v0, s8, 0
	v_mbcnt_hi_u32_b32 v0, s9, v0
	v_cmp_eq_u32_e32 vcc, 0, v0
	s_waitcnt vmcnt(0)
	buffer_inv sc1
	s_and_saveexec_b64 s[10:11], vcc
	s_cbranch_execz .LBB0_273
	s_bcnt1_i32_b64 s3, s[8:9]
	v_mov_b32_e32 v0, 0x2000
	v_mov_b32_e32 v1, s3
	global_atomic_add v0, v1, s[6:7] offset:1024

; DI unsigned xb_ld(unsigned* p)              { return __hip_atomic_load(p, __ATOMIC_RELAXED, __HIP_MEMORY_SCOPE_AGENT); }
; DI unsigned xb_add(unsigned* p, unsigned v) { return __hip_atomic_fetch_add(p, v, __ATOMIC_RELAXED, __HIP_MEMORY_SCOPE_AGENT); }
; #define XB_SPIN(cond, bar) do { unsigned _sp = 0; while (cond) { __builtin_amdgcn_s_sleep(1); \
;     if ((++_sp & 255u) == 0u) { if (xb_ld(&(bar)[XB_TMO])) break; if (_sp > XB_SPIN_CAP) { atomicAdd(&(bar)[XB_TMO], 1u); break; } } } } while (0)
; DI void xcd_barrier(unsigned* bar, volatile __attribute__((address_space(3))) unsigned* st) {
;     ...
;             __builtin_amdgcn_fence(__ATOMIC_RELEASE, "agent");
;             asm volatile("s_waitcnt vmcnt(0)" ::: "memory");
;             const unsigned og = xb_add(&bar[XB_TOP], 1u);
;             const unsigned tg = og / nx;
;             if (og + 1u == (tg + 1u) * nx) xb_add(&bar[XB_TOPGEN], 1u);
;             else XB_SPIN(xb_ld(&bar[XB_TOPGEN]) == tg, bar);
.LBB0_337:
	s_andn2_saveexec_b64 s[8:9], s[8:9]
	s_cbranch_execz .LBB0_357
	s_mov_b64 s[8:9], exec
	buffer_wbl2 sc1
	s_waitcnt lgkmcnt(0)
	s_waitcnt vmcnt(0)
	v_mov_b32_e32 v2, 0x34e5000
	v_mov_b32_e32 v3, 1
	global_atomic_add v2, v3, s[70:71] offset:1280
	v_mul_u32_u24_e32 v4, 3, v1

; DI unsigned xb_ld(unsigned* p)              { return __hip_atomic_load(p, __ATOMIC_RELAXED, __HIP_MEMORY_SCOPE_AGENT); }
; DI unsigned xb_add(unsigned* p, unsigned v) { return __hip_atomic_fetch_add(p, v, __ATOMIC_RELAXED, __HIP_MEMORY_SCOPE_AGENT); }
; #define XB_SPIN(cond, bar) do { unsigned _sp = 0; while (cond) { __builtin_amdgcn_s_sleep(1); \
;     if ((++_sp & 255u) == 0u) { if (xb_ld(&(bar)[XB_TMO])) break; if (_sp > XB_SPIN_CAP) { atomicAdd(&(bar)[XB_TMO], 1u); break; } } } } while (0)
; DI void xcd_barrier(unsigned* bar, volatile __attribute__((address_space(3))) unsigned* st) {
;     ...
;             else XB_SPIN(xb_ld(&bar[XB_TOPGEN]) == tg, bar);
;             __builtin_amdgcn_fence(__ATOMIC_ACQUIRE, "agent");
;             xb_add(&bar[XB_XGEN(x)], 1u);
;             asm volatile("s_waitcnt vmcnt(0)" ::: "memory");
.Ltopf_d3:
	s_mov_b64 s[8:9], exec
.LBB0_354:
	s_or_b64 exec, exec, s[8:9]
	s_mov_b64 s[8:9], exec
	v_mbcnt_lo_u32_b32 v0, s8, 0
	v_mbcnt_hi_u32_b32 v0, s9, v0
	v_cmp_eq_u32_e32 vcc, 0, v0
	s_waitcnt vmcnt(0)
	buffer_inv sc1
	s_and_saveexec_b64 s[10:11], vcc
	s_cbranch_execz .LBB0_356
	s_bcnt1_i32_b64 s3, s[8:9]
	v_mov_b32_e32 v0, 0x2000
	v_mov_b32_e32 v1, s3
	global_atomic_add v0, v1, s[6:7] offset:1024

; DI unsigned xb_ld(unsigned* p)              { return __hip_atomic_load(p, __ATOMIC_RELAXED, __HIP_MEMORY_SCOPE_AGENT); }
; DI unsigned xb_add(unsigned* p, unsigned v) { return __hip_atomic_fetch_add(p, v, __ATOMIC_RELAXED, __HIP_MEMORY_SCOPE_AGENT); }
; #define XB_SPIN(cond, bar) do { unsigned _sp = 0; while (cond) { __builtin_amdgcn_s_sleep(1); \
;     if ((++_sp & 255u) == 0u) { if (xb_ld(&(bar)[XB_TMO])) break; if (_sp > XB_SPIN_CAP) { atomicAdd(&(bar)[XB_TMO], 1u); break; } } } } while (0)
; DI void xcd_barrier(unsigned* bar, volatile __attribute__((address_space(3))) unsigned* st) {
;     ...
;             __builtin_amdgcn_fence(__ATOMIC_RELEASE, "agent");
;             asm volatile("s_waitcnt vmcnt(0)" ::: "memory");
;             const unsigned og = xb_add(&bar[XB_TOP], 1u);
;             const unsigned tg = og / nx;
;             if (og + 1u == (tg + 1u) * nx) xb_add(&bar[XB_TOPGEN], 1u);
;             else XB_SPIN(xb_ld(&bar[XB_TOPGEN]) == tg, bar);
.LBB0_414:
	s_andn2_saveexec_b64 s[6:7], s[6:7]
	s_cbranch_execz .LBB0_434
	s_mov_b64 s[6:7], exec
	buffer_wbl2 sc1
	s_waitcnt lgkmcnt(0)
	s_waitcnt vmcnt(0)
	v_mov_b32_e32 v2, 0x34e5000
	v_mov_b32_e32 v3, 1
	global_atomic_add v2, v3, s[70:71] offset:1280
	v_mul_u32_u24_e32 v4, 4, v1

; DI unsigned xb_ld(unsigned* p)              { return __hip_atomic_load(p, __ATOMIC_RELAXED, __HIP_MEMORY_SCOPE_AGENT); }
; DI unsigned xb_add(unsigned* p, unsigned v) { return __hip_atomic_fetch_add(p, v, __ATOMIC_RELAXED, __HIP_MEMORY_SCOPE_AGENT); }
; #define XB_SPIN(cond, bar) do { unsigned _sp = 0; while (cond) { __builtin_amdgcn_s_sleep(1); \
;     if ((++_sp & 255u) == 0u) { if (xb_ld(&(bar)[XB_TMO])) break; if (_sp > XB_SPIN_CAP) { atomicAdd(&(bar)[XB_TMO], 1u); break; } } } } while (0)
; DI void xcd_barrier(unsigned* bar, volatile __attribute__((address_space(3))) unsigned* st) {
;     ...
;             else XB_SPIN(xb_ld(&bar[XB_TOPGEN]) == tg, bar);
;             __builtin_amdgcn_fence(__ATOMIC_ACQUIRE, "agent");
;             xb_add(&bar[XB_XGEN(x)], 1u);
;             asm volatile("s_waitcnt vmcnt(0)" ::: "memory");
.Ltopf_d4:
	s_mov_b64 s[6:7], exec
.LBB0_431:
	s_or_b64 exec, exec, s[6:7]
	s_mov_b64 s[6:7], exec
	v_mbcnt_lo_u32_b32 v0, s6, 0
	v_mbcnt_hi_u32_b32 v0, s7, v0
	v_cmp_eq_u32_e32 vcc, 0, v0
	s_waitcnt vmcnt(0)
	buffer_inv sc1
	s_and_saveexec_b64 s[8:9], vcc
	s_cbranch_execz .LBB0_433
	s_bcnt1_i32_b64 s3, s[6:7]
	v_mov_b32_e32 v0, 0x2000
	v_mov_b32_e32 v1, s3
	global_atomic_add v0, v1, s[4:5] offset:1024

; DI unsigned xb_ld(unsigned* p)              { return __hip_atomic_load(p, __ATOMIC_RELAXED, __HIP_MEMORY_SCOPE_AGENT); }
; DI unsigned xb_add(unsigned* p, unsigned v) { return __hip_atomic_fetch_add(p, v, __ATOMIC_RELAXED, __HIP_MEMORY_SCOPE_AGENT); }
; #define XB_SPIN(cond, bar) do { unsigned _sp = 0; while (cond) { __builtin_amdgcn_s_sleep(1); \
;     if ((++_sp & 255u) == 0u) { if (xb_ld(&(bar)[XB_TMO])) break; if (_sp > XB_SPIN_CAP) { atomicAdd(&(bar)[XB_TMO], 1u); break; } } } } while (0)
; DI void xcd_barrier(unsigned* bar, volatile __attribute__((address_space(3))) unsigned* st) {
;     ...
;             __builtin_amdgcn_fence(__ATOMIC_RELEASE, "agent");
;             asm volatile("s_waitcnt vmcnt(0)" ::: "memory");
;             const unsigned og = xb_add(&bar[XB_TOP], 1u);
;             const unsigned tg = og / nx;
;             if (og + 1u == (tg + 1u) * nx) xb_add(&bar[XB_TOPGEN], 1u);
;             else XB_SPIN(xb_ld(&bar[XB_TOPGEN]) == tg, bar);
.LBB0_504:
	s_andn2_saveexec_b64 s[8:9], s[8:9]
	s_cbranch_execz .LBB0_524
	s_mov_b64 s[8:9], exec
	buffer_wbl2 sc1
	s_waitcnt lgkmcnt(0)
	s_waitcnt vmcnt(0)
	v_mov_b32_e32 v2, 0x34e5000
	v_mov_b32_e32 v3, 1
	global_atomic_add v2, v3, s[70:71] offset:1280
	v_mul_u32_u24_e32 v4, 5, v1

; DI unsigned xb_ld(unsigned* p)              { return __hip_atomic_load(p, __ATOMIC_RELAXED, __HIP_MEMORY_SCOPE_AGENT); }
; DI unsigned xb_add(unsigned* p, unsigned v) { return __hip_atomic_fetch_add(p, v, __ATOMIC_RELAXED, __HIP_MEMORY_SCOPE_AGENT); }
; #define XB_SPIN(cond, bar) do { unsigned _sp = 0; while (cond) { __builtin_amdgcn_s_sleep(1); \
;     if ((++_sp & 255u) == 0u) { if (xb_ld(&(bar)[XB_TMO])) break; if (_sp > XB_SPIN_CAP) { atomicAdd(&(bar)[XB_TMO], 1u); break; } } } } while (0)
; DI void xcd_barrier(unsigned* bar, volatile __attribute__((address_space(3))) unsigned* st) {
;     ...
;             else XB_SPIN(xb_ld(&bar[XB_TOPGEN]) == tg, bar);
;             __builtin_amdgcn_fence(__ATOMIC_ACQUIRE, "agent");
;             xb_add(&bar[XB_XGEN(x)], 1u);
;             asm volatile("s_waitcnt vmcnt(0)" ::: "memory");
.Ltopf_d5:
	s_mov_b64 s[8:9], exec
.LBB0_521:
	s_or_b64 exec, exec, s[8:9]
	s_mov_b64 s[8:9], exec
	v_mbcnt_lo_u32_b32 v0, s8, 0
	v_mbcnt_hi_u32_b32 v0, s9, v0
	v_cmp_eq_u32_e32 vcc, 0, v0
	s_waitcnt vmcnt(0)
	buffer_inv sc1
	s_and_saveexec_b64 s[10:11], vcc
	s_cbranch_execz .LBB0_523
	s_bcnt1_i32_b64 s3, s[8:9]
	v_mov_b32_e32 v0, 0x2000
	v_mov_b32_e32 v1, s3
	global_atomic_add v0, v1, s[4:5] offset:1024

; DI unsigned xb_ld(unsigned* p)              { return __hip_atomic_load(p, __ATOMIC_RELAXED, __HIP_MEMORY_SCOPE_AGENT); }
; DI unsigned xb_add(unsigned* p, unsigned v) { return __hip_atomic_fetch_add(p, v, __ATOMIC_RELAXED, __HIP_MEMORY_SCOPE_AGENT); }
; #define XB_SPIN(cond, bar) do { unsigned _sp = 0; while (cond) { __builtin_amdgcn_s_sleep(1); \
;     if ((++_sp & 255u) == 0u) { if (xb_ld(&(bar)[XB_TMO])) break; if (_sp > XB_SPIN_CAP) { atomicAdd(&(bar)[XB_TMO], 1u); break; } } } } while (0)
; DI void xcd_barrier(unsigned* bar, volatile __attribute__((address_space(3))) unsigned* st) {
;     ...
;             __builtin_amdgcn_fence(__ATOMIC_RELEASE, "agent");
;             asm volatile("s_waitcnt vmcnt(0)" ::: "memory");
;             const unsigned og = xb_add(&bar[XB_TOP], 1u);
;             const unsigned tg = og / nx;
;             if (og + 1u == (tg + 1u) * nx) xb_add(&bar[XB_TOPGEN], 1u);
;             else XB_SPIN(xb_ld(&bar[XB_TOPGEN]) == tg, bar);
.LBB0_612:
	s_andn2_saveexec_b64 s[6:7], s[6:7]
	s_cbranch_execz .LBB0_632
	s_mov_b64 s[6:7], exec
	buffer_wbl2 sc1
	s_waitcnt lgkmcnt(0)
	s_waitcnt vmcnt(0)
	v_mov_b32_e32 v2, 0x34e5000
	v_mov_b32_e32 v3, 1
	global_atomic_add v2, v3, s[70:71] offset:1280
	v_mul_u32_u24_e32 v4, 6, v1

; DI unsigned xb_ld(unsigned* p)              { return __hip_atomic_load(p, __ATOMIC_RELAXED, __HIP_MEMORY_SCOPE_AGENT); }
; DI unsigned xb_add(unsigned* p, unsigned v) { return __hip_atomic_fetch_add(p, v, __ATOMIC_RELAXED, __HIP_MEMORY_SCOPE_AGENT); }
; #define XB_SPIN(cond, bar) do { unsigned _sp = 0; while (cond) { __builtin_amdgcn_s_sleep(1); \
;     if ((++_sp & 255u) == 0u) { if (xb_ld(&(bar)[XB_TMO])) break; if (_sp > XB_SPIN_CAP) { atomicAdd(&(bar)[XB_TMO], 1u); break; } } } } while (0)
; DI void xcd_barrier(unsigned* bar, volatile __attribute__((address_space(3))) unsigned* st) {
;     ...
;             else XB_SPIN(xb_ld(&bar[XB_TOPGEN]) == tg, bar);
;             __builtin_amdgcn_fence(__ATOMIC_ACQUIRE, "agent");
;             xb_add(&bar[XB_XGEN(x)], 1u);
;             asm volatile("s_waitcnt vmcnt(0)" ::: "memory");
.Ltopf_d6:
	s_mov_b64 s[6:7], exec
.LBB0_629:
	s_or_b64 exec, exec, s[6:7]
	s_mov_b64 s[6:7], exec
	v_mbcnt_lo_u32_b32 v0, s6, 0
	v_mbcnt_hi_u32_b32 v0, s7, v0
	v_cmp_eq_u32_e32 vcc, 0, v0
	s_waitcnt vmcnt(0)
	buffer_inv sc1
	s_and_saveexec_b64 s[8:9], vcc
	s_cbranch_execz .LBB0_631
	s_bcnt1_i32_b64 s3, s[6:7]
	v_mov_b32_e32 v0, 0x2000
	v_mov_b32_e32 v1, s3
	global_atomic_add v0, v1, s[4:5] offset:1024

; DI unsigned xb_ld(unsigned* p)              { return __hip_atomic_load(p, __ATOMIC_RELAXED, __HIP_MEMORY_SCOPE_AGENT); }
; DI unsigned xb_add(unsigned* p, unsigned v) { return __hip_atomic_fetch_add(p, v, __ATOMIC_RELAXED, __HIP_MEMORY_SCOPE_AGENT); }
; #define XB_SPIN(cond, bar) do { unsigned _sp = 0; while (cond) { __builtin_amdgcn_s_sleep(1); \
;     if ((++_sp & 255u) == 0u) { if (xb_ld(&(bar)[XB_TMO])) break; if (_sp > XB_SPIN_CAP) { atomicAdd(&(bar)[XB_TMO], 1u); break; } } } } while (0)
; DI void xcd_barrier(unsigned* bar, volatile __attribute__((address_space(3))) unsigned* st) {
;     ...
;             __builtin_amdgcn_fence(__ATOMIC_RELEASE, "agent");
;             asm volatile("s_waitcnt vmcnt(0)" ::: "memory");
;             const unsigned og = xb_add(&bar[XB_TOP], 1u);
;             const unsigned tg = og / nx;
;             if (og + 1u == (tg + 1u) * nx) xb_add(&bar[XB_TOPGEN], 1u);
;             else XB_SPIN(xb_ld(&bar[XB_TOPGEN]) == tg, bar);
.LBB0_694:
	s_andn2_saveexec_b64 s[6:7], s[6:7]
	s_cbranch_execz .LBB0_714
	s_mov_b64 s[6:7], exec
	buffer_wbl2 sc1
	s_waitcnt lgkmcnt(0)
	s_waitcnt vmcnt(0)
	v_mov_b32_e32 v2, 0x34e5000
	v_mov_b32_e32 v3, 1
	global_atomic_add v2, v3, s[70:71] offset:1280
	v_mul_u32_u24_e32 v4, 7, v1

; DI unsigned xb_ld(unsigned* p)              { return __hip_atomic_load(p, __ATOMIC_RELAXED, __HIP_MEMORY_SCOPE_AGENT); }
; DI unsigned xb_add(unsigned* p, unsigned v) { return __hip_atomic_fetch_add(p, v, __ATOMIC_RELAXED, __HIP_MEMORY_SCOPE_AGENT); }
; #define XB_SPIN(cond, bar) do { unsigned _sp = 0; while (cond) { __builtin_amdgcn_s_sleep(1); \
;     if ((++_sp & 255u) == 0u) { if (xb_ld(&(bar)[XB_TMO])) break; if (_sp > XB_SPIN_CAP) { atomicAdd(&(bar)[XB_TMO], 1u); break; } } } } while (0)
; DI void xcd_barrier(unsigned* bar, volatile __attribute__((address_space(3))) unsigned* st) {
;     ...
;             else XB_SPIN(xb_ld(&bar[XB_TOPGEN]) == tg, bar);
;             __builtin_amdgcn_fence(__ATOMIC_ACQUIRE, "agent");
;             xb_add(&bar[XB_XGEN(x)], 1u);
;             asm volatile("s_waitcnt vmcnt(0)" ::: "memory");
.Ltopf_d7:
	s_mov_b64 s[6:7], exec
.LBB0_711:
	s_or_b64 exec, exec, s[6:7]
	s_mov_b64 s[6:7], exec
	v_mbcnt_lo_u32_b32 v0, s6, 0
	v_mbcnt_hi_u32_b32 v0, s7, v0
	v_cmp_eq_u32_e32 vcc, 0, v0
	s_waitcnt vmcnt(0)
	buffer_inv sc1
	s_and_saveexec_b64 s[8:9], vcc
	s_cbranch_execz .LBB0_713
	s_bcnt1_i32_b64 s3, s[6:7]
	v_mov_b32_e32 v0, 0x2000
	v_mov_b32_e32 v1, s3
	global_atomic_add v0, v1, s[4:5] offset:1024

; DI unsigned xb_ld(unsigned* p)              { return __hip_atomic_load(p, __ATOMIC_RELAXED, __HIP_MEMORY_SCOPE_AGENT); }
; DI unsigned xb_add(unsigned* p, unsigned v) { return __hip_atomic_fetch_add(p, v, __ATOMIC_RELAXED, __HIP_MEMORY_SCOPE_AGENT); }
; #define XB_SPIN(cond, bar) do { unsigned _sp = 0; while (cond) { __builtin_amdgcn_s_sleep(1); \
;     if ((++_sp & 255u) == 0u) { if (xb_ld(&(bar)[XB_TMO])) break; if (_sp > XB_SPIN_CAP) { atomicAdd(&(bar)[XB_TMO], 1u); break; } } } } while (0)
; DI void xcd_barrier(unsigned* bar, volatile __attribute__((address_space(3))) unsigned* st) {
;     ...
;             __builtin_amdgcn_fence(__ATOMIC_RELEASE, "agent");
;             asm volatile("s_waitcnt vmcnt(0)" ::: "memory");
;             const unsigned og = xb_add(&bar[XB_TOP], 1u);
;             const unsigned tg = og / nx;
;             if (og + 1u == (tg + 1u) * nx) xb_add(&bar[XB_TOPGEN], 1u);
;             else XB_SPIN(xb_ld(&bar[XB_TOPGEN]) == tg, bar);
.LBB0_815:
	s_andn2_saveexec_b64 s[6:7], s[6:7]
	s_cbranch_execz .LBB0_835
	s_mov_b64 s[6:7], exec
	buffer_wbl2 sc1
	s_waitcnt lgkmcnt(0)
	s_waitcnt vmcnt(0)
	v_mov_b32_e32 v2, 0x34e5000
	v_mov_b32_e32 v3, 1
	global_atomic_add v2, v3, s[70:71] offset:1280
	v_mul_u32_u24_e32 v4, 8, v1

; DI unsigned xb_ld(unsigned* p)              { return __hip_atomic_load(p, __ATOMIC_RELAXED, __HIP_MEMORY_SCOPE_AGENT); }
; DI unsigned xb_add(unsigned* p, unsigned v) { return __hip_atomic_fetch_add(p, v, __ATOMIC_RELAXED, __HIP_MEMORY_SCOPE_AGENT); }
; #define XB_SPIN(cond, bar) do { unsigned _sp = 0; while (cond) { __builtin_amdgcn_s_sleep(1); \
;     if ((++_sp & 255u) == 0u) { if (xb_ld(&(bar)[XB_TMO])) break; if (_sp > XB_SPIN_CAP) { atomicAdd(&(bar)[XB_TMO], 1u); break; } } } } while (0)
; DI void xcd_barrier(unsigned* bar, volatile __attribute__((address_space(3))) unsigned* st) {
;     ...
;             else XB_SPIN(xb_ld(&bar[XB_TOPGEN]) == tg, bar);
;             __builtin_amdgcn_fence(__ATOMIC_ACQUIRE, "agent");
;             xb_add(&bar[XB_XGEN(x)], 1u);
;             asm volatile("s_waitcnt vmcnt(0)" ::: "memory");
.Ltopf_d8:
	s_mov_b64 s[6:7], exec
.LBB0_832:
	s_or_b64 exec, exec, s[6:7]
	s_mov_b64 s[6:7], exec
	v_mbcnt_lo_u32_b32 v0, s6, 0
	v_mbcnt_hi_u32_b32 v0, s7, v0
	v_cmp_eq_u32_e32 vcc, 0, v0
	s_waitcnt vmcnt(0)
	buffer_inv sc1
	s_and_saveexec_b64 s[8:9], vcc
	s_cbranch_execz .LBB0_834
	s_bcnt1_i32_b64 s3, s[6:7]
	v_mov_b32_e32 v0, 0x2000
	v_mov_b32_e32 v1, s3
	global_atomic_add v0, v1, s[4:5] offset:1024

; DI unsigned xb_ld(unsigned* p)              { return __hip_atomic_load(p, __ATOMIC_RELAXED, __HIP_MEMORY_SCOPE_AGENT); }
; DI unsigned xb_add(unsigned* p, unsigned v) { return __hip_atomic_fetch_add(p, v, __ATOMIC_RELAXED, __HIP_MEMORY_SCOPE_AGENT); }
; #define XB_SPIN(cond, bar) do { unsigned _sp = 0; while (cond) { __builtin_amdgcn_s_sleep(1); \
;     if ((++_sp & 255u) == 0u) { if (xb_ld(&(bar)[XB_TMO])) break; if (_sp > XB_SPIN_CAP) { atomicAdd(&(bar)[XB_TMO], 1u); break; } } } } while (0)
; DI void xcd_barrier(unsigned* bar, volatile __attribute__((address_space(3))) unsigned* st) {
;     ...
;             __builtin_amdgcn_fence(__ATOMIC_RELEASE, "agent");
;             asm volatile("s_waitcnt vmcnt(0)" ::: "memory");
;             const unsigned og = xb_add(&bar[XB_TOP], 1u);
;             const unsigned tg = og / nx;
;             if (og + 1u == (tg + 1u) * nx) xb_add(&bar[XB_TOPGEN], 1u);
;             else XB_SPIN(xb_ld(&bar[XB_TOPGEN]) == tg, bar);
.LBB0_891:
	s_andn2_saveexec_b64 s[8:9], s[8:9]
	s_cbranch_execz .LBB0_911
	s_mov_b64 s[8:9], exec
	buffer_wbl2 sc1
	s_waitcnt lgkmcnt(0)
	s_waitcnt vmcnt(0)
	v_mov_b32_e32 v2, 0x34e5000
	v_mov_b32_e32 v3, 1
	global_atomic_add v2, v3, s[70:71] offset:1280
	v_mul_u32_u24_e32 v4, 9, v1

; DI unsigned xb_ld(unsigned* p)              { return __hip_atomic_load(p, __ATOMIC_RELAXED, __HIP_MEMORY_SCOPE_AGENT); }
; DI unsigned xb_add(unsigned* p, unsigned v) { return __hip_atomic_fetch_add(p, v, __ATOMIC_RELAXED, __HIP_MEMORY_SCOPE_AGENT); }
; #define XB_SPIN(cond, bar) do { unsigned _sp = 0; while (cond) { __builtin_amdgcn_s_sleep(1); \
;     if ((++_sp & 255u) == 0u) { if (xb_ld(&(bar)[XB_TMO])) break; if (_sp > XB_SPIN_CAP) { atomicAdd(&(bar)[XB_TMO], 1u); break; } } } } while (0)
; DI void xcd_barrier(unsigned* bar, volatile __attribute__((address_space(3))) unsigned* st) {
;     ...
;             else XB_SPIN(xb_ld(&bar[XB_TOPGEN]) == tg, bar);
;             __builtin_amdgcn_fence(__ATOMIC_ACQUIRE, "agent");
;             xb_add(&bar[XB_XGEN(x)], 1u);
;             asm volatile("s_waitcnt vmcnt(0)" ::: "memory");
.Ltopf_d9:
	s_mov_b64 s[8:9], exec
.LBB0_908:
	s_or_b64 exec, exec, s[8:9]
	s_mov_b64 s[8:9], exec
	v_mbcnt_lo_u32_b32 v0, s8, 0
	v_mbcnt_hi_u32_b32 v0, s9, v0
	v_cmp_eq_u32_e32 vcc, 0, v0
	s_waitcnt vmcnt(0)
	buffer_inv sc1
	s_and_saveexec_b64 s[10:11], vcc
	s_cbranch_execz .LBB0_910
	s_bcnt1_i32_b64 s3, s[8:9]
	v_mov_b32_e32 v0, 0x2000
	v_mov_b32_e32 v1, s3
	global_atomic_add v0, v1, s[6:7] offset:1024

; DI unsigned xb_ld(unsigned* p)              { return __hip_atomic_load(p, __ATOMIC_RELAXED, __HIP_MEMORY_SCOPE_AGENT); }
; DI unsigned xb_add(unsigned* p, unsigned v) { return __hip_atomic_fetch_add(p, v, __ATOMIC_RELAXED, __HIP_MEMORY_SCOPE_AGENT); }
; #define XB_SPIN(cond, bar) do { unsigned _sp = 0; while (cond) { __builtin_amdgcn_s_sleep(1); \
;     if ((++_sp & 255u) == 0u) { if (xb_ld(&(bar)[XB_TMO])) break; if (_sp > XB_SPIN_CAP) { atomicAdd(&(bar)[XB_TMO], 1u); break; } } } } while (0)
; DI void xcd_barrier(unsigned* bar, volatile __attribute__((address_space(3))) unsigned* st) {
;     ...
;             __builtin_amdgcn_fence(__ATOMIC_RELEASE, "agent");
;             asm volatile("s_waitcnt vmcnt(0)" ::: "memory");
;             const unsigned og = xb_add(&bar[XB_TOP], 1u);
;             const unsigned tg = og / nx;
;             if (og + 1u == (tg + 1u) * nx) xb_add(&bar[XB_TOPGEN], 1u);
;             else XB_SPIN(xb_ld(&bar[XB_TOPGEN]) == tg, bar);
.LBB0_967:
	s_andn2_saveexec_b64 s[8:9], s[8:9]
	s_cbranch_execz .LBB0_987
	s_mov_b64 s[8:9], exec
	buffer_wbl2 sc1
	s_waitcnt lgkmcnt(0)
	s_waitcnt vmcnt(0)
	v_mov_b32_e32 v2, 0x34e5000
	v_mov_b32_e32 v3, 1
	global_atomic_add v2, v3, s[70:71] offset:1280
	v_mul_u32_u24_e32 v4, 10, v1

; DI unsigned xb_ld(unsigned* p)              { return __hip_atomic_load(p, __ATOMIC_RELAXED, __HIP_MEMORY_SCOPE_AGENT); }
; DI unsigned xb_add(unsigned* p, unsigned v) { return __hip_atomic_fetch_add(p, v, __ATOMIC_RELAXED, __HIP_MEMORY_SCOPE_AGENT); }
; #define XB_SPIN(cond, bar) do { unsigned _sp = 0; while (cond) { __builtin_amdgcn_s_sleep(1); \
;     if ((++_sp & 255u) == 0u) { if (xb_ld(&(bar)[XB_TMO])) break; if (_sp > XB_SPIN_CAP) { atomicAdd(&(bar)[XB_TMO], 1u); break; } } } } while (0)
; DI void xcd_barrier(unsigned* bar, volatile __attribute__((address_space(3))) unsigned* st) {
;     ...
;             else XB_SPIN(xb_ld(&bar[XB_TOPGEN]) == tg, bar);
;             __builtin_amdgcn_fence(__ATOMIC_ACQUIRE, "agent");
;             xb_add(&bar[XB_XGEN(x)], 1u);
;             asm volatile("s_waitcnt vmcnt(0)" ::: "memory");
.Ltopf_d10:
	s_mov_b64 s[8:9], exec
.LBB0_984:
	s_or_b64 exec, exec, s[8:9]
	s_mov_b64 s[8:9], exec
	v_mbcnt_lo_u32_b32 v0, s8, 0
	v_mbcnt_hi_u32_b32 v0, s9, v0
	v_cmp_eq_u32_e32 vcc, 0, v0
	s_waitcnt vmcnt(0)
	buffer_inv sc1
	s_and_saveexec_b64 s[10:11], vcc
	s_cbranch_execz .LBB0_986
	s_bcnt1_i32_b64 s3, s[8:9]
	v_mov_b32_e32 v0, 0x2000
	v_mov_b32_e32 v1, s3
	global_atomic_add v0, v1, s[6:7] offset:1024

; DI unsigned xb_ld(unsigned* p)              { return __hip_atomic_load(p, __ATOMIC_RELAXED, __HIP_MEMORY_SCOPE_AGENT); }
; DI unsigned xb_add(unsigned* p, unsigned v) { return __hip_atomic_fetch_add(p, v, __ATOMIC_RELAXED, __HIP_MEMORY_SCOPE_AGENT); }
; #define XB_SPIN(cond, bar) do { unsigned _sp = 0; while (cond) { __builtin_amdgcn_s_sleep(1); \
;     if ((++_sp & 255u) == 0u) { if (xb_ld(&(bar)[XB_TMO])) break; if (_sp > XB_SPIN_CAP) { atomicAdd(&(bar)[XB_TMO], 1u); break; } } } } while (0)
; DI void xcd_barrier(unsigned* bar, volatile __attribute__((address_space(3))) unsigned* st) {
;     ...
;             __builtin_amdgcn_fence(__ATOMIC_RELEASE, "agent");
;             asm volatile("s_waitcnt vmcnt(0)" ::: "memory");
;             const unsigned og = xb_add(&bar[XB_TOP], 1u);
;             const unsigned tg = og / nx;
;             if (og + 1u == (tg + 1u) * nx) xb_add(&bar[XB_TOPGEN], 1u);
;             else XB_SPIN(xb_ld(&bar[XB_TOPGEN]) == tg, bar);
.LBB0_1030:
	s_andn2_saveexec_b64 s[8:9], s[8:9]
	s_cbranch_execz .LBB0_1050
	s_mov_b64 s[8:9], exec
	buffer_wbl2 sc1
	s_waitcnt lgkmcnt(0)
	s_waitcnt vmcnt(0)
	v_mov_b32_e32 v2, 0x34e5000
	v_mov_b32_e32 v3, 1
	global_atomic_add v2, v3, s[70:71] offset:1280
	v_mul_u32_u24_e32 v4, 11, v1

; DI unsigned xb_ld(unsigned* p)              { return __hip_atomic_load(p, __ATOMIC_RELAXED, __HIP_MEMORY_SCOPE_AGENT); }
; DI unsigned xb_add(unsigned* p, unsigned v) { return __hip_atomic_fetch_add(p, v, __ATOMIC_RELAXED, __HIP_MEMORY_SCOPE_AGENT); }
; #define XB_SPIN(cond, bar) do { unsigned _sp = 0; while (cond) { __builtin_amdgcn_s_sleep(1); \
;     if ((++_sp & 255u) == 0u) { if (xb_ld(&(bar)[XB_TMO])) break; if (_sp > XB_SPIN_CAP) { atomicAdd(&(bar)[XB_TMO], 1u); break; } } } } while (0)
; DI void xcd_barrier(unsigned* bar, volatile __attribute__((address_space(3))) unsigned* st) {
;     ...
;             else XB_SPIN(xb_ld(&bar[XB_TOPGEN]) == tg, bar);
;             __builtin_amdgcn_fence(__ATOMIC_ACQUIRE, "agent");
;             xb_add(&bar[XB_XGEN(x)], 1u);
;             asm volatile("s_waitcnt vmcnt(0)" ::: "memory");
.Ltopf_d11:
	s_mov_b64 s[8:9], exec
.LBB0_1047:
	s_or_b64 exec, exec, s[8:9]
	s_mov_b64 s[8:9], exec
	v_mbcnt_lo_u32_b32 v0, s8, 0
	v_mbcnt_hi_u32_b32 v0, s9, v0
	v_cmp_eq_u32_e32 vcc, 0, v0
	s_waitcnt vmcnt(0)
	buffer_inv sc1
	s_and_saveexec_b64 s[12:13], vcc
	s_cbranch_execz .LBB0_1049
	s_bcnt1_i32_b64 s3, s[8:9]
	v_mov_b32_e32 v0, 0x2000
	v_mov_b32_e32 v1, s3
	global_atomic_add v0, v1, s[6:7] offset:1024

; DI unsigned xb_ld(unsigned* p)              { return __hip_atomic_load(p, __ATOMIC_RELAXED, __HIP_MEMORY_SCOPE_AGENT); }
; DI unsigned xb_add(unsigned* p, unsigned v) { return __hip_atomic_fetch_add(p, v, __ATOMIC_RELAXED, __HIP_MEMORY_SCOPE_AGENT); }
; #define XB_SPIN(cond, bar) do { unsigned _sp = 0; while (cond) { __builtin_amdgcn_s_sleep(1); \
;     if ((++_sp & 255u) == 0u) { if (xb_ld(&(bar)[XB_TMO])) break; if (_sp > XB_SPIN_CAP) { atomicAdd(&(bar)[XB_TMO], 1u); break; } } } } while (0)
; DI void xcd_barrier(unsigned* bar, volatile __attribute__((address_space(3))) unsigned* st) {
;     ...
;             __builtin_amdgcn_fence(__ATOMIC_RELEASE, "agent");
;             asm volatile("s_waitcnt vmcnt(0)" ::: "memory");
;             const unsigned og = xb_add(&bar[XB_TOP], 1u);
;             const unsigned tg = og / nx;
;             if (og + 1u == (tg + 1u) * nx) xb_add(&bar[XB_TOPGEN], 1u);
;             else XB_SPIN(xb_ld(&bar[XB_TOPGEN]) == tg, bar);
.LBB0_1124:
	s_andn2_saveexec_b64 s[8:9], s[8:9]
	s_cbranch_execz .LBB0_1144
	s_mov_b64 s[8:9], exec
	buffer_wbl2 sc1
	s_waitcnt lgkmcnt(0)
	s_waitcnt vmcnt(0)
	v_mov_b32_e32 v2, 0x34e5000
	v_mov_b32_e32 v3, 1
	global_atomic_add v2, v3, s[70:71] offset:1280
	v_mul_u32_u24_e32 v4, 12, v1

; DI unsigned xb_ld(unsigned* p)              { return __hip_atomic_load(p, __ATOMIC_RELAXED, __HIP_MEMORY_SCOPE_AGENT); }
; DI unsigned xb_add(unsigned* p, unsigned v) { return __hip_atomic_fetch_add(p, v, __ATOMIC_RELAXED, __HIP_MEMORY_SCOPE_AGENT); }
; #define XB_SPIN(cond, bar) do { unsigned _sp = 0; while (cond) { __builtin_amdgcn_s_sleep(1); \
;     if ((++_sp & 255u) == 0u) { if (xb_ld(&(bar)[XB_TMO])) break; if (_sp > XB_SPIN_CAP) { atomicAdd(&(bar)[XB_TMO], 1u); break; } } } } while (0)
; DI void xcd_barrier(unsigned* bar, volatile __attribute__((address_space(3))) unsigned* st) {
;     ...
;             else XB_SPIN(xb_ld(&bar[XB_TOPGEN]) == tg, bar);
;             __builtin_amdgcn_fence(__ATOMIC_ACQUIRE, "agent");
;             xb_add(&bar[XB_XGEN(x)], 1u);
;             asm volatile("s_waitcnt vmcnt(0)" ::: "memory");
.Ltopf_d12:
	s_mov_b64 s[8:9], exec
.LBB0_1141:
	s_or_b64 exec, exec, s[8:9]
	s_mov_b64 s[8:9], exec
	v_mbcnt_lo_u32_b32 v0, s8, 0
	v_mbcnt_hi_u32_b32 v0, s9, v0
	v_cmp_eq_u32_e32 vcc, 0, v0
	s_waitcnt vmcnt(0)
	buffer_inv sc1
	s_and_saveexec_b64 s[16:17], vcc
	s_cbranch_execz .LBB0_1143
	s_bcnt1_i32_b64 s3, s[8:9]
	v_mov_b32_e32 v0, 0x2000
	v_mov_b32_e32 v1, s3
	global_atomic_add v0, v1, s[6:7] offset:1024

; DI unsigned xb_ld(unsigned* p)              { return __hip_atomic_load(p, __ATOMIC_RELAXED, __HIP_MEMORY_SCOPE_AGENT); }
; DI unsigned xb_add(unsigned* p, unsigned v) { return __hip_atomic_fetch_add(p, v, __ATOMIC_RELAXED, __HIP_MEMORY_SCOPE_AGENT); }
; #define XB_SPIN(cond, bar) do { unsigned _sp = 0; while (cond) { __builtin_amdgcn_s_sleep(1); \
;     if ((++_sp & 255u) == 0u) { if (xb_ld(&(bar)[XB_TMO])) break; if (_sp > XB_SPIN_CAP) { atomicAdd(&(bar)[XB_TMO], 1u); break; } } } } while (0)
; DI void xcd_barrier(unsigned* bar, volatile __attribute__((address_space(3))) unsigned* st) {
;     ...
;             __builtin_amdgcn_fence(__ATOMIC_RELEASE, "agent");
;             asm volatile("s_waitcnt vmcnt(0)" ::: "memory");
;             const unsigned og = xb_add(&bar[XB_TOP], 1u);
;             const unsigned tg = og / nx;
;             if (og + 1u == (tg + 1u) * nx) xb_add(&bar[XB_TOPGEN], 1u);
;             else XB_SPIN(xb_ld(&bar[XB_TOPGEN]) == tg, bar);
.LBB0_1183:
	s_andn2_saveexec_b64 s[8:9], s[8:9]
	s_cbranch_execz .LBB0_1203
	s_mov_b64 s[8:9], exec
	buffer_wbl2 sc1
	s_waitcnt lgkmcnt(0)
	s_waitcnt vmcnt(0)
	v_mov_b32_e32 v2, 0x34e5000
	v_mov_b32_e32 v3, 1
	global_atomic_add v2, v3, s[70:71] offset:1280
	v_mul_u32_u24_e32 v4, 13, v1

; DI unsigned xb_ld(unsigned* p)              { return __hip_atomic_load(p, __ATOMIC_RELAXED, __HIP_MEMORY_SCOPE_AGENT); }
; DI unsigned xb_add(unsigned* p, unsigned v) { return __hip_atomic_fetch_add(p, v, __ATOMIC_RELAXED, __HIP_MEMORY_SCOPE_AGENT); }
; #define XB_SPIN(cond, bar) do { unsigned _sp = 0; while (cond) { __builtin_amdgcn_s_sleep(1); \
;     if ((++_sp & 255u) == 0u) { if (xb_ld(&(bar)[XB_TMO])) break; if (_sp > XB_SPIN_CAP) { atomicAdd(&(bar)[XB_TMO], 1u); break; } } } } while (0)
; DI void xcd_barrier(unsigned* bar, volatile __attribute__((address_space(3))) unsigned* st) {
;     ...
;             else XB_SPIN(xb_ld(&bar[XB_TOPGEN]) == tg, bar);
;             __builtin_amdgcn_fence(__ATOMIC_ACQUIRE, "agent");
;             xb_add(&bar[XB_XGEN(x)], 1u);
;             asm volatile("s_waitcnt vmcnt(0)" ::: "memory");
.Ltopf_d13:
	s_mov_b64 s[8:9], exec
.LBB0_1200:
	s_or_b64 exec, exec, s[8:9]
	s_mov_b64 s[8:9], exec
	v_mbcnt_lo_u32_b32 v0, s8, 0
	v_mbcnt_hi_u32_b32 v0, s9, v0
	v_cmp_eq_u32_e32 vcc, 0, v0
	s_waitcnt vmcnt(0)
	buffer_inv sc1
	s_and_saveexec_b64 s[12:13], vcc
	s_cbranch_execz .LBB0_1202
	s_bcnt1_i32_b64 s3, s[8:9]
	v_mov_b32_e32 v0, 0x2000
	v_mov_b32_e32 v1, s3
	global_atomic_add v0, v1, s[6:7] offset:1024

; DI unsigned xb_ld(unsigned* p)              { return __hip_atomic_load(p, __ATOMIC_RELAXED, __HIP_MEMORY_SCOPE_AGENT); }
; DI unsigned xb_add(unsigned* p, unsigned v) { return __hip_atomic_fetch_add(p, v, __ATOMIC_RELAXED, __HIP_MEMORY_SCOPE_AGENT); }
; #define XB_SPIN(cond, bar) do { unsigned _sp = 0; while (cond) { __builtin_amdgcn_s_sleep(1); \
;     if ((++_sp & 255u) == 0u) { if (xb_ld(&(bar)[XB_TMO])) break; if (_sp > XB_SPIN_CAP) { atomicAdd(&(bar)[XB_TMO], 1u); break; } } } } while (0)
; DI void xcd_barrier(unsigned* bar, volatile __attribute__((address_space(3))) unsigned* st) {
;     ...
;             __builtin_amdgcn_fence(__ATOMIC_RELEASE, "agent");
;             asm volatile("s_waitcnt vmcnt(0)" ::: "memory");
;             const unsigned og = xb_add(&bar[XB_TOP], 1u);
;             const unsigned tg = og / nx;
;             if (og + 1u == (tg + 1u) * nx) xb_add(&bar[XB_TOPGEN], 1u);
;             else XB_SPIN(xb_ld(&bar[XB_TOPGEN]) == tg, bar);
.LBB0_1263:
	s_andn2_saveexec_b64 s[4:5], s[4:5]
	s_cbranch_execz .LBB0_1283
	s_mov_b64 s[4:5], exec
	buffer_wbl2 sc1
	s_waitcnt lgkmcnt(0)
	s_waitcnt vmcnt(0)
	v_mov_b32_e32 v2, 0x34e5000
	v_mov_b32_e32 v3, 1
	global_atomic_add v2, v3, s[70:71] offset:1280
	v_mul_u32_u24_e32 v4, 14, v1

; DI unsigned xb_ld(unsigned* p)              { return __hip_atomic_load(p, __ATOMIC_RELAXED, __HIP_MEMORY_SCOPE_AGENT); }
; DI unsigned xb_add(unsigned* p, unsigned v) { return __hip_atomic_fetch_add(p, v, __ATOMIC_RELAXED, __HIP_MEMORY_SCOPE_AGENT); }
; #define XB_SPIN(cond, bar) do { unsigned _sp = 0; while (cond) { __builtin_amdgcn_s_sleep(1); \
;     if ((++_sp & 255u) == 0u) { if (xb_ld(&(bar)[XB_TMO])) break; if (_sp > XB_SPIN_CAP) { atomicAdd(&(bar)[XB_TMO], 1u); break; } } } } while (0)
; DI void xcd_barrier(unsigned* bar, volatile __attribute__((address_space(3))) unsigned* st) {
;     ...
;             else XB_SPIN(xb_ld(&bar[XB_TOPGEN]) == tg, bar);
;             __builtin_amdgcn_fence(__ATOMIC_ACQUIRE, "agent");
;             xb_add(&bar[XB_XGEN(x)], 1u);
;             asm volatile("s_waitcnt vmcnt(0)" ::: "memory");
.Ltopf_d14:
	s_mov_b64 s[4:5], exec
.LBB0_1280:
	s_or_b64 exec, exec, s[4:5]
	s_mov_b64 s[4:5], exec
	v_mbcnt_lo_u32_b32 v0, s4, 0
	v_mbcnt_hi_u32_b32 v0, s5, v0
	v_cmp_eq_u32_e32 vcc, 0, v0
	s_waitcnt vmcnt(0)
	buffer_inv sc1
	s_and_saveexec_b64 s[6:7], vcc
	s_cbranch_execz .LBB0_1282
	s_bcnt1_i32_b64 s4, s[4:5]
	v_mov_b32_e32 v0, 0x2000
	v_mov_b32_e32 v1, s4
	global_atomic_add v0, v1, s[2:3] offset:1024
